# EpiResid row sum-of-squares reduction: 4 of 5 ds_bpermute steps replaced by DPP adds (phases 4,6,11)
# baseline (speedup 1.0000x reference)
.LBB0_559:
	v_or_b32_e32 v8, s18, v34
	v_lshlrev_b32_e32 v98, 12, v8
	s_waitcnt lgkmcnt(0)
	v_lshl_add_u64 v[2:3], v[30:31], 0, v[98:99]
	global_load_dwordx4 v[38:41], v[2:3], off nt
	v_add_u32_e32 v98, 8, v8
	v_lshlrev_b64 v[2:3], 12, v[98:99]
	v_add_u32_e32 v98, 16, v8
	v_lshl_add_u64 v[2:3], v[30:31], 0, v[2:3]
	v_lshlrev_b64 v[4:5], 12, v[98:99]
	v_add_u32_e32 v98, 24, v8
	global_load_dwordx4 v[26:29], v[2:3], off nt
	v_lshl_add_u64 v[2:3], v[30:31], 0, v[4:5]
	v_lshlrev_b64 v[4:5], 12, v[98:99]
	v_or_b32_e32 v98, 32, v8
	v_lshl_add_u64 v[4:5], v[30:31], 0, v[4:5]
	v_lshlrev_b64 v[6:7], 12, v[98:99]
	v_add_u32_e32 v98, 40, v8
	global_load_dwordx4 v[22:25], v[2:3], off nt
	global_load_dwordx4 v[18:21], v[4:5], off nt
	v_lshlrev_b64 v[4:5], 12, v[98:99]
	v_add_u32_e32 v98, 48, v8
	v_lshl_add_u64 v[2:3], v[30:31], 0, v[6:7]
	v_lshl_add_u64 v[4:5], v[30:31], 0, v[4:5]
	v_lshlrev_b64 v[6:7], 12, v[98:99]
	v_add_u32_e32 v98, 56, v8
	global_load_dwordx4 v[14:17], v[2:3], off nt
	global_load_dwordx4 v[10:13], v[4:5], off nt
	v_lshlrev_b64 v[4:5], 12, v[98:99]
	v_lshl_add_u64 v[2:3], v[30:31], 0, v[6:7]
	v_lshl_add_u64 v[4:5], v[30:31], 0, v[4:5]
	global_load_dwordx4 v[6:9], v[2:3], off nt
	s_nop 0
	global_load_dwordx4 v[2:5], v[4:5], off nt
	v_or_b32_e32 v36, s18, v1
	s_movk_i32 s18, 0x210
	v_mad_u32_u24 v37, v36, s18, v131
	ds_read_b128 v[42:45], v37
	v_lshlrev_b32_e32 v98, 7, v36
	s_waitcnt vmcnt(7) lgkmcnt(0)
	v_pk_add_f32 v[42:43], v[38:39], v[42:43]
	s_nop 0
	v_mul_f32_e32 v37, v43, v43
	v_pk_add_f32 v[40:41], v[40:41], v[44:45]
	v_fmac_f32_e32 v37, v42, v42
	v_fmac_f32_e32 v37, v40, v40
	v_fmac_f32_e32 v37, v41, v41
	v_lshl_add_u64 v[44:45], v[32:33], 0, v[98:99]
	v_cvt_pk_bf16_f32 v42, v42, v43
	v_cvt_pk_bf16_f32 v43, v40, v41
	global_store_dwordx2 v[44:45], v[42:43], off
	s_waitcnt lgkmcnt(0)
	s_nop 1
	v_add_f32_dpp v37, v37, v37 quad_perm:[1,0,3,2] row_mask:0xf bank_mask:0xf
	s_waitcnt lgkmcnt(0)
	s_nop 1
	v_add_f32_dpp v37, v37, v37 quad_perm:[2,3,0,1] row_mask:0xf bank_mask:0xf
	s_waitcnt lgkmcnt(0)
	s_nop 1
	v_add_f32_dpp v37, v37, v37 row_half_mirror row_mask:0xf bank_mask:0xf
	s_waitcnt lgkmcnt(0)
	s_nop 1
	v_add_f32_dpp v37, v37, v37 row_mirror row_mask:0xf bank_mask:0xf
	ds_bpermute_b32 v38, v136, v37
	s_and_saveexec_b64 s[18:19], s[4:5]
	s_cbranch_execz .LBB0_561
	v_or_b32_e32 v39, s8, v36
	v_lshlrev_b32_e32 v39, 6, v39
	s_waitcnt lgkmcnt(0)
	v_add_f32_e32 v98, v37, v38
	global_store_dwordx2 v39, v[98:99], s[14:15]
.LBB0_561:
	s_or_b64 exec, exec, s[18:19]
	v_mul_u32_u24_e32 v37, 0x210, v36
	v_add_u32_e32 v37, v37, v131
	s_waitcnt lgkmcnt(0)
	ds_read_b128 v[38:41], v37 offset:4224
	v_add_u32_e32 v42, 8, v36
	v_lshlrev_b32_e32 v98, 7, v42
	s_waitcnt vmcnt(7) lgkmcnt(0)
	v_pk_add_f32 v[38:39], v[26:27], v[38:39]
	s_nop 0
	v_mul_f32_e32 v26, v39, v39
	v_pk_add_f32 v[40:41], v[28:29], v[40:41]
	v_fmac_f32_e32 v26, v38, v38
	v_fmac_f32_e32 v26, v40, v40
	v_fmac_f32_e32 v26, v41, v41
	v_cvt_pk_bf16_f32 v38, v38, v39
	v_cvt_pk_bf16_f32 v39, v40, v41
	s_waitcnt lgkmcnt(0)
	s_nop 1
	v_add_f32_dpp v27, v26, v26 quad_perm:[1,0,3,2] row_mask:0xf bank_mask:0xf
	v_or_b32_e32 v26, s8, v42
	v_lshrrev_b32_e32 v29, 3, v26
	s_waitcnt lgkmcnt(0)
	s_nop 1
	v_add_f32_dpp v27, v27, v27 quad_perm:[2,3,0,1] row_mask:0xf bank_mask:0xf
	v_and_b32_e32 v28, 0x1ffffff0, v29
	v_add_u32_e32 v28, v28, v35
	v_ashrrev_i32_e32 v29, 31, v28
	v_lshlrev_b64 v[28:29], 14, v[28:29]
	s_waitcnt lgkmcnt(0)
	s_nop 1
	v_add_f32_dpp v27, v27, v27 row_half_mirror row_mask:0xf bank_mask:0xf
	v_lshl_add_u64 v[28:29], s[92:93], 0, v[28:29]
	v_lshl_add_u64 v[42:43], v[28:29], 0, v[98:99]
	v_lshlrev_b32_e32 v98, 1, v104
	v_lshl_add_u64 v[42:43], v[42:43], 0, v[98:99]
	s_waitcnt lgkmcnt(0)
	s_nop 1
	v_add_f32_dpp v27, v27, v27 row_mirror row_mask:0xf bank_mask:0xf
	ds_bpermute_b32 v28, v136, v27
	global_store_dwordx2 v[42:43], v[38:39], off
	s_and_saveexec_b64 s[18:19], s[4:5]
	s_cbranch_execz .LBB0_563
	v_lshlrev_b32_e32 v29, 6, v26
	s_waitcnt lgkmcnt(0)
	v_add_f32_e32 v26, v27, v28
	v_mov_b32_e32 v27, v99
	global_store_dwordx2 v29, v[26:27], s[14:15]
.LBB0_563:
	s_or_b64 exec, exec, s[18:19]
	v_add_u32_e32 v27, 16, v36
	v_or_b32_e32 v26, s8, v27
	ds_read_b128 v[38:41], v37 offset:8448
	s_waitcnt lgkmcnt(1)
	v_lshrrev_b32_e32 v28, 3, v26
	v_and_b32_e32 v28, 0x1ffffff0, v28
	v_add_u32_e32 v28, v28, v35
	v_ashrrev_i32_e32 v29, 31, v28
	v_lshlrev_b64 v[28:29], 14, v[28:29]
	s_waitcnt vmcnt(7) lgkmcnt(0)
	v_pk_add_f32 v[22:23], v[22:23], v[38:39]
	v_lshl_add_u64 v[28:29], s[92:93], 0, v[28:29]
	v_lshlrev_b32_e32 v38, 7, v27
	v_mov_b32_e32 v39, v99
	v_lshl_add_u64 v[28:29], v[28:29], 0, v[38:39]
	v_cvt_pk_bf16_f32 v38, v22, v23
	v_mul_f32_e32 v23, v23, v23
	v_pk_add_f32 v[24:25], v[24:25], v[40:41]
	v_fmac_f32_e32 v23, v22, v22
	v_fmac_f32_e32 v23, v24, v24
	v_fmac_f32_e32 v23, v25, v25
	v_lshl_add_u64 v[28:29], v[28:29], 0, v[98:99]
	v_cvt_pk_bf16_f32 v39, v24, v25
	global_store_dwordx2 v[28:29], v[38:39], off
	s_waitcnt lgkmcnt(0)
	s_nop 1
	v_add_f32_dpp v22, v23, v23 quad_perm:[1,0,3,2] row_mask:0xf bank_mask:0xf
	s_waitcnt lgkmcnt(0)
	s_nop 1
	v_add_f32_dpp v22, v22, v22 quad_perm:[2,3,0,1] row_mask:0xf bank_mask:0xf
	s_waitcnt lgkmcnt(0)
	s_nop 1
	v_add_f32_dpp v22, v22, v22 row_half_mirror row_mask:0xf bank_mask:0xf
	s_waitcnt lgkmcnt(0)
	s_nop 1
	v_add_f32_dpp v22, v22, v22 row_mirror row_mask:0xf bank_mask:0xf
	ds_bpermute_b32 v23, v136, v22
	s_and_saveexec_b64 s[18:19], s[4:5]
	s_cbranch_execz .LBB0_565
	v_lshlrev_b32_e32 v24, 6, v26
	s_waitcnt lgkmcnt(0)
	v_add_f32_e32 v22, v22, v23
	v_mov_b32_e32 v23, v99
	global_store_dwordx2 v24, v[22:23], s[14:15]
.LBB0_565:
	s_or_b64 exec, exec, s[18:19]
	ds_read_b128 v[24:27], v37 offset:12672
	s_waitcnt lgkmcnt(1)
	v_add_u32_e32 v23, 24, v36
	v_or_b32_e32 v22, s8, v23
	s_waitcnt vmcnt(7) lgkmcnt(0)
	v_pk_add_f32 v[18:19], v[18:19], v[24:25]
	v_lshrrev_b32_e32 v24, 3, v22
	v_and_b32_e32 v24, 0x1ffffff0, v24
	v_add_u32_e32 v24, v24, v35
	v_ashrrev_i32_e32 v25, 31, v24
	v_lshlrev_b64 v[24:25], 14, v[24:25]
	v_pk_add_f32 v[20:21], v[20:21], v[26:27]
	v_lshl_add_u64 v[24:25], s[92:93], 0, v[24:25]
	v_lshlrev_b32_e32 v26, 7, v23
	v_mov_b32_e32 v27, v99
	v_lshl_add_u64 v[24:25], v[24:25], 0, v[26:27]
	v_cvt_pk_bf16_f32 v26, v18, v19
	v_mul_f32_e32 v19, v19, v19
	v_fmac_f32_e32 v19, v18, v18
	v_fmac_f32_e32 v19, v20, v20
	v_fmac_f32_e32 v19, v21, v21
	v_lshl_add_u64 v[24:25], v[24:25], 0, v[98:99]
	v_cvt_pk_bf16_f32 v27, v20, v21
	global_store_dwordx2 v[24:25], v[26:27], off
	s_waitcnt lgkmcnt(0)
	s_nop 1
	v_add_f32_dpp v18, v19, v19 quad_perm:[1,0,3,2] row_mask:0xf bank_mask:0xf
	s_waitcnt lgkmcnt(0)
	s_nop 1
	v_add_f32_dpp v18, v18, v18 quad_perm:[2,3,0,1] row_mask:0xf bank_mask:0xf
	s_waitcnt lgkmcnt(0)
	s_nop 1
	v_add_f32_dpp v18, v18, v18 row_half_mirror row_mask:0xf bank_mask:0xf
	s_waitcnt lgkmcnt(0)
	s_nop 1
	v_add_f32_dpp v18, v18, v18 row_mirror row_mask:0xf bank_mask:0xf
	ds_bpermute_b32 v19, v136, v18
	s_and_saveexec_b64 s[18:19], s[4:5]
	s_cbranch_execz .LBB0_567
	v_lshlrev_b32_e32 v20, 6, v22
	s_waitcnt lgkmcnt(0)
	v_add_f32_e32 v18, v18, v19
	v_mov_b32_e32 v19, v99
	global_store_dwordx2 v20, v[18:19], s[14:15]
.LBB0_567:
	s_or_b64 exec, exec, s[18:19]
	ds_read_b128 v[20:23], v37 offset:16896
	s_waitcnt lgkmcnt(1)
	v_or_b32_e32 v19, 32, v36
	v_or_b32_e32 v18, s8, v19
	s_waitcnt vmcnt(7) lgkmcnt(0)
	v_pk_add_f32 v[14:15], v[14:15], v[20:21]
	v_lshrrev_b32_e32 v20, 3, v18
	v_and_b32_e32 v20, 0x1ffffff0, v20
	v_add_u32_e32 v20, v20, v35
	v_ashrrev_i32_e32 v21, 31, v20
	v_lshlrev_b64 v[20:21], 14, v[20:21]
	v_pk_add_f32 v[16:17], v[16:17], v[22:23]
	v_lshl_add_u64 v[20:21], s[92:93], 0, v[20:21]
	v_lshlrev_b32_e32 v22, 7, v19
	v_mov_b32_e32 v23, v99
	v_lshl_add_u64 v[20:21], v[20:21], 0, v[22:23]
	v_cvt_pk_bf16_f32 v22, v14, v15
	v_mul_f32_e32 v15, v15, v15
	v_fmac_f32_e32 v15, v14, v14
	v_fmac_f32_e32 v15, v16, v16
	v_fmac_f32_e32 v15, v17, v17
	v_lshl_add_u64 v[20:21], v[20:21], 0, v[98:99]
	v_cvt_pk_bf16_f32 v23, v16, v17
	global_store_dwordx2 v[20:21], v[22:23], off
	s_waitcnt lgkmcnt(0)
	s_nop 1
	v_add_f32_dpp v14, v15, v15 quad_perm:[1,0,3,2] row_mask:0xf bank_mask:0xf
	s_waitcnt lgkmcnt(0)
	s_nop 1
	v_add_f32_dpp v14, v14, v14 quad_perm:[2,3,0,1] row_mask:0xf bank_mask:0xf
	s_waitcnt lgkmcnt(0)
	s_nop 1
	v_add_f32_dpp v14, v14, v14 row_half_mirror row_mask:0xf bank_mask:0xf
	s_waitcnt lgkmcnt(0)
	s_nop 1
	v_add_f32_dpp v14, v14, v14 row_mirror row_mask:0xf bank_mask:0xf
	ds_bpermute_b32 v15, v136, v14
	s_and_saveexec_b64 s[18:19], s[4:5]
	s_cbranch_execz .LBB0_569
	v_lshlrev_b32_e32 v16, 6, v18
	s_waitcnt lgkmcnt(0)
	v_add_f32_e32 v14, v14, v15
	v_mov_b32_e32 v15, v99
	global_store_dwordx2 v16, v[14:15], s[14:15]
.LBB0_569:
	s_or_b64 exec, exec, s[18:19]
	ds_read_b128 v[16:19], v37 offset:21120
	s_waitcnt lgkmcnt(1)
	v_add_u32_e32 v15, 40, v36
	v_add_u32_e32 v14, s8, v15
	v_lshlrev_b32_e32 v15, 7, v15
	s_waitcnt vmcnt(7) lgkmcnt(0)
	v_pk_add_f32 v[10:11], v[10:11], v[16:17]
	v_lshrrev_b32_e32 v16, 3, v14
	v_and_b32_e32 v16, 0x1ffffff0, v16
	v_add_u32_e32 v16, v16, v35
	v_ashrrev_i32_e32 v17, 31, v16
	v_lshlrev_b64 v[16:17], 14, v[16:17]
	v_pk_add_f32 v[12:13], v[12:13], v[18:19]
	v_lshl_add_u64 v[16:17], s[92:93], 0, v[16:17]
	v_and_b32_e32 v18, 0x3f80, v15
	v_mov_b32_e32 v19, v99
	v_lshl_add_u64 v[16:17], v[16:17], 0, v[18:19]
	v_cvt_pk_bf16_f32 v18, v10, v11
	v_mul_f32_e32 v11, v11, v11
	v_fmac_f32_e32 v11, v10, v10
	v_fmac_f32_e32 v11, v12, v12
	v_fmac_f32_e32 v11, v13, v13
	v_lshl_add_u64 v[16:17], v[16:17], 0, v[98:99]
	v_cvt_pk_bf16_f32 v19, v12, v13
	global_store_dwordx2 v[16:17], v[18:19], off
	s_waitcnt lgkmcnt(0)
	s_nop 1
	v_add_f32_dpp v10, v11, v11 quad_perm:[1,0,3,2] row_mask:0xf bank_mask:0xf
	s_waitcnt lgkmcnt(0)
	s_nop 1
	v_add_f32_dpp v10, v10, v10 quad_perm:[2,3,0,1] row_mask:0xf bank_mask:0xf
	s_waitcnt lgkmcnt(0)
	s_nop 1
	v_add_f32_dpp v10, v10, v10 row_half_mirror row_mask:0xf bank_mask:0xf
	s_waitcnt lgkmcnt(0)
	s_nop 1
	v_add_f32_dpp v10, v10, v10 row_mirror row_mask:0xf bank_mask:0xf
	ds_bpermute_b32 v11, v136, v10
	s_and_saveexec_b64 s[18:19], s[4:5]
	s_cbranch_execz .LBB0_571
	v_lshlrev_b32_e32 v12, 6, v14
	s_waitcnt lgkmcnt(0)
	v_add_f32_e32 v10, v10, v11
	v_mov_b32_e32 v11, v99
	global_store_dwordx2 v12, v[10:11], s[14:15]
.LBB0_571:
	s_or_b64 exec, exec, s[18:19]
	ds_read_b128 v[12:15], v37 offset:25344
	s_waitcnt lgkmcnt(1)
	v_add_u32_e32 v11, 48, v36
	v_add_u32_e32 v10, s8, v11
	v_lshlrev_b32_e32 v11, 7, v11
	s_waitcnt vmcnt(7) lgkmcnt(0)
	v_pk_add_f32 v[6:7], v[6:7], v[12:13]
	v_lshrrev_b32_e32 v12, 3, v10
	v_and_b32_e32 v12, 0x1ffffff0, v12
	v_add_u32_e32 v12, v12, v35
	v_ashrrev_i32_e32 v13, 31, v12
	v_lshlrev_b64 v[12:13], 14, v[12:13]
	v_pk_add_f32 v[8:9], v[8:9], v[14:15]
	v_lshl_add_u64 v[12:13], s[92:93], 0, v[12:13]
	v_and_b32_e32 v14, 0x3f80, v11
	v_mov_b32_e32 v15, v99
	v_lshl_add_u64 v[12:13], v[12:13], 0, v[14:15]
	v_cvt_pk_bf16_f32 v14, v6, v7
	v_mul_f32_e32 v7, v7, v7
	v_fmac_f32_e32 v7, v6, v6
	v_fmac_f32_e32 v7, v8, v8
	v_fmac_f32_e32 v7, v9, v9
	v_lshl_add_u64 v[12:13], v[12:13], 0, v[98:99]
	v_cvt_pk_bf16_f32 v15, v8, v9
	global_store_dwordx2 v[12:13], v[14:15], off
	s_waitcnt lgkmcnt(0)
	s_nop 1
	v_add_f32_dpp v6, v7, v7 quad_perm:[1,0,3,2] row_mask:0xf bank_mask:0xf
	s_waitcnt lgkmcnt(0)
	s_nop 1
	v_add_f32_dpp v6, v6, v6 quad_perm:[2,3,0,1] row_mask:0xf bank_mask:0xf
	s_waitcnt lgkmcnt(0)
	s_nop 1
	v_add_f32_dpp v6, v6, v6 row_half_mirror row_mask:0xf bank_mask:0xf
	s_waitcnt lgkmcnt(0)
	s_nop 1
	v_add_f32_dpp v6, v6, v6 row_mirror row_mask:0xf bank_mask:0xf
	ds_bpermute_b32 v7, v136, v6
	s_and_saveexec_b64 s[18:19], s[4:5]
	s_cbranch_execz .LBB0_573
	v_lshlrev_b32_e32 v8, 6, v10
	s_waitcnt lgkmcnt(0)
	v_add_f32_e32 v6, v6, v7
	v_mov_b32_e32 v7, v99
	global_store_dwordx2 v8, v[6:7], s[14:15]
.LBB0_573:
	s_or_b64 exec, exec, s[18:19]
	ds_read_b128 v[8:11], v37 offset:29568
	s_waitcnt lgkmcnt(1)
	v_add_u32_e32 v7, 56, v36
	v_add_u32_e32 v6, s8, v7
	v_lshlrev_b32_e32 v7, 7, v7
	s_waitcnt vmcnt(7) lgkmcnt(0)
	v_pk_add_f32 v[2:3], v[2:3], v[8:9]
	v_lshrrev_b32_e32 v8, 3, v6
	v_and_b32_e32 v8, 0x1ffffff0, v8
	v_add_u32_e32 v8, v8, v35
	v_ashrrev_i32_e32 v9, 31, v8
	v_lshlrev_b64 v[8:9], 14, v[8:9]
	v_pk_add_f32 v[4:5], v[4:5], v[10:11]
	v_lshl_add_u64 v[8:9], s[92:93], 0, v[8:9]
	v_and_b32_e32 v10, 0x3f80, v7
	v_mov_b32_e32 v11, v99
	v_lshl_add_u64 v[8:9], v[8:9], 0, v[10:11]
	v_cvt_pk_bf16_f32 v10, v2, v3
	v_mul_f32_e32 v3, v3, v3
	v_fmac_f32_e32 v3, v2, v2
	v_fmac_f32_e32 v3, v4, v4
	v_fmac_f32_e32 v3, v5, v5
	v_lshl_add_u64 v[8:9], v[8:9], 0, v[98:99]
	v_cvt_pk_bf16_f32 v11, v4, v5
	global_store_dwordx2 v[8:9], v[10:11], off
	s_waitcnt lgkmcnt(0)
	s_nop 1
	v_add_f32_dpp v2, v3, v3 quad_perm:[1,0,3,2] row_mask:0xf bank_mask:0xf
	s_waitcnt lgkmcnt(0)
	s_nop 1
	v_add_f32_dpp v2, v2, v2 quad_perm:[2,3,0,1] row_mask:0xf bank_mask:0xf
	s_waitcnt lgkmcnt(0)
	s_nop 1
	v_add_f32_dpp v2, v2, v2 row_half_mirror row_mask:0xf bank_mask:0xf
	s_waitcnt lgkmcnt(0)
	s_nop 1
	v_add_f32_dpp v2, v2, v2 row_mirror row_mask:0xf bank_mask:0xf
	ds_bpermute_b32 v3, v136, v2
	s_and_saveexec_b64 s[18:19], s[4:5]
	s_cbranch_execz .LBB0_558
	v_lshlrev_b32_e32 v4, 6, v6
	s_waitcnt lgkmcnt(0)
	v_add_f32_e32 v98, v2, v3
	global_store_dwordx2 v4, v[98:99], s[14:15]
	s_branch .LBB0_558

.LBB0_763:
	v_or_b32_e32 v24, s16, v20
	v_add_u32_e32 v10, 8, v24
	s_waitcnt lgkmcnt(0)
	v_lshrrev_b32_e32 v8, 3, v10
	v_and_b32_e32 v8, 0xffffff0, v8
	v_add_u32_e32 v8, v8, v21
	v_ashrrev_i32_e32 v9, 31, v8
	v_lshlrev_b64 v[8:9], 14, v[8:9]
	v_lshlrev_b32_e32 v10, 7, v10
	v_lshl_add_u64 v[8:9], s[92:93], 0, v[8:9]
	v_and_b32_e32 v10, 0x3f80, v10
	v_mov_b32_e32 v11, v115
	v_add_u32_e32 v12, 16, v24
	v_lshl_add_u64 v[8:9], v[8:9], 0, v[10:11]
	v_lshrrev_b32_e32 v10, 3, v12
	v_and_b32_e32 v10, 0xffffff0, v10
	v_add_u32_e32 v10, v10, v21
	v_ashrrev_i32_e32 v11, 31, v10
	v_lshlrev_b64 v[10:11], 14, v[10:11]
	v_lshlrev_b32_e32 v12, 7, v12
	v_lshl_add_u64 v[10:11], s[92:93], 0, v[10:11]
	v_and_b32_e32 v12, 0x3f80, v12
	v_mov_b32_e32 v13, v115
	v_add_u32_e32 v14, 24, v24
	v_lshl_add_u64 v[10:11], v[10:11], 0, v[12:13]
	v_lshrrev_b32_e32 v12, 3, v14
	v_and_b32_e32 v12, 0xffffff0, v12
	v_add_u32_e32 v12, v12, v21
	v_lshlrev_b32_e32 v6, 7, v24
	v_ashrrev_i32_e32 v13, 31, v12
	v_and_b32_e32 v6, 0x2f80, v6
	v_mov_b32_e32 v7, v115
	v_lshlrev_b64 v[12:13], 14, v[12:13]
	v_lshlrev_b32_e32 v14, 7, v14
	v_lshl_add_u64 v[6:7], v[2:3], 0, v[6:7]
	v_lshl_add_u64 v[12:13], s[92:93], 0, v[12:13]
	v_and_b32_e32 v14, 0x3f80, v14
	v_mov_b32_e32 v15, v115
	v_lshl_add_u64 v[6:7], v[6:7], 0, v[114:115]
	v_lshl_add_u64 v[12:13], v[12:13], 0, v[14:15]
	v_lshl_add_u64 v[8:9], v[8:9], 0, v[114:115]
	v_lshl_add_u64 v[10:11], v[10:11], 0, v[114:115]
	v_lshl_add_u64 v[12:13], v[12:13], 0, v[114:115]
	global_load_dwordx2 v[28:29], v[6:7], off
	global_load_dwordx2 v[18:19], v[8:9], off
	global_load_dwordx2 v[16:17], v[10:11], off
	global_load_dwordx2 v[14:15], v[12:13], off
	v_add_u32_e32 v10, 40, v24
	v_lshrrev_b32_e32 v8, 3, v10
	v_and_b32_e32 v8, 0xffffff0, v8
	v_add_u32_e32 v8, v8, v21
	v_ashrrev_i32_e32 v9, 31, v8
	v_lshlrev_b64 v[8:9], 14, v[8:9]
	v_lshlrev_b32_e32 v10, 7, v10
	v_lshl_add_u64 v[8:9], s[92:93], 0, v[8:9]
	v_and_b32_e32 v10, 0x3f80, v10
	v_mov_b32_e32 v11, v115
	v_add_u32_e32 v12, 48, v24
	v_lshl_add_u64 v[8:9], v[8:9], 0, v[10:11]
	v_lshrrev_b32_e32 v10, 3, v12
	v_and_b32_e32 v10, 0xffffff0, v10
	v_add_u32_e32 v10, v10, v21
	v_ashrrev_i32_e32 v11, 31, v10
	v_lshlrev_b64 v[10:11], 14, v[10:11]
	v_lshlrev_b32_e32 v12, 7, v12
	v_lshl_add_u64 v[10:11], s[92:93], 0, v[10:11]
	v_and_b32_e32 v12, 0x3f80, v12
	v_mov_b32_e32 v13, v115
	v_lshl_add_u64 v[10:11], v[10:11], 0, v[12:13]
	v_add_u32_e32 v12, 56, v24
	v_lshl_add_u64 v[22:23], v[10:11], 0, v[114:115]
	v_lshrrev_b32_e32 v10, 3, v12
	v_and_b32_e32 v10, 0xffffff0, v10
	v_add_u32_e32 v10, v10, v21
	v_ashrrev_i32_e32 v11, 31, v10
	v_lshlrev_b64 v[10:11], 14, v[10:11]
	v_lshlrev_b32_e32 v12, 7, v12
	v_add_co_u32_e32 v6, vcc, s19, v6
	v_lshl_add_u64 v[10:11], s[92:93], 0, v[10:11]
	v_and_b32_e32 v12, 0x3f80, v12
	v_addc_co_u32_e32 v7, vcc, 0, v7, vcc
	v_lshl_add_u64 v[8:9], v[8:9], 0, v[114:115]
	v_lshl_add_u64 v[10:11], v[10:11], 0, v[12:13]
	v_lshl_add_u64 v[24:25], v[10:11], 0, v[114:115]
	global_load_dwordx2 v[12:13], v[6:7], off
	global_load_dwordx2 v[10:11], v[8:9], off
	s_nop 0
	global_load_dwordx2 v[8:9], v[22:23], off
	global_load_dwordx2 v[6:7], v[24:25], off
	v_or_b32_e32 v22, s16, v1
	v_mad_u32_u24 v23, v22, s20, v162
	ds_read_b128 v[24:27], v23
	s_waitcnt vmcnt(7)
	v_and_b32_e32 v31, 0xffff0000, v28
	v_lshlrev_b32_e32 v30, 16, v28
	v_and_b32_e32 v33, 0xffff0000, v29
	v_lshlrev_b32_e32 v32, 16, v29
	s_waitcnt lgkmcnt(0)
	v_pk_add_f32 v[28:29], v[24:25], v[30:31]
	v_pk_add_f32 v[26:27], v[26:27], v[32:33]
	v_mul_f32_e32 v23, v29, v29
	v_fmac_f32_e32 v23, v28, v28
	v_fmac_f32_e32 v23, v26, v26
	v_fmac_f32_e32 v23, v27, v27
	v_lshlrev_b32_e32 v30, 7, v22
	v_mov_b32_e32 v31, v115
	v_lshl_add_u64 v[30:31], v[4:5], 0, v[30:31]
	v_cvt_pk_bf16_f32 v28, v28, v29
	s_waitcnt lgkmcnt(0)
	s_nop 1
	v_add_f32_dpp v23, v23, v23 quad_perm:[1,0,3,2] row_mask:0xf bank_mask:0xf
	v_cvt_pk_bf16_f32 v29, v26, v27
	global_store_dwordx2 v[30:31], v[28:29], off
	s_waitcnt lgkmcnt(0)
	s_nop 1
	v_add_f32_dpp v23, v23, v23 quad_perm:[2,3,0,1] row_mask:0xf bank_mask:0xf
	s_waitcnt lgkmcnt(0)
	s_nop 1
	v_add_f32_dpp v23, v23, v23 row_half_mirror row_mask:0xf bank_mask:0xf
	s_waitcnt lgkmcnt(0)
	s_nop 1
	v_add_f32_dpp v23, v23, v23 row_mirror row_mask:0xf bank_mask:0xf
	ds_bpermute_b32 v24, v168, v23
	s_and_saveexec_b64 s[16:17], s[4:5]
	s_cbranch_execz .LBB0_765
	s_waitcnt lgkmcnt(0)
	v_add_f32_e32 v24, v23, v24
	v_or_b32_e32 v23, s10, v22
	v_lshlrev_b32_e32 v23, 6, v23
	v_mov_b32_e32 v25, v115
	global_store_dwordx2 v23, v[24:25], s[6:7]
.LBB0_765:
	s_or_b64 exec, exec, s[16:17]
	v_mul_u32_u24_e32 v23, 0x210, v22
	v_add_u32_e32 v23, v23, v162
	s_waitcnt lgkmcnt(0)
	ds_read_b128 v[24:27], v23 offset:4224
	s_waitcnt vmcnt(7)
	v_and_b32_e32 v29, 0xffff0000, v18
	v_lshlrev_b32_e32 v28, 16, v18
	v_and_b32_e32 v31, 0xffff0000, v19
	v_lshlrev_b32_e32 v30, 16, v19
	s_waitcnt lgkmcnt(0)
	v_pk_add_f32 v[28:29], v[24:25], v[28:29]
	v_pk_add_f32 v[26:27], v[26:27], v[30:31]
	v_mul_f32_e32 v18, v29, v29
	v_fmac_f32_e32 v18, v28, v28
	v_fmac_f32_e32 v18, v26, v26
	v_fmac_f32_e32 v18, v27, v27
	v_add_u32_e32 v30, 8, v22
	v_cvt_pk_bf16_f32 v28, v28, v29
	v_cvt_pk_bf16_f32 v29, v26, v27
	s_waitcnt lgkmcnt(0)
	s_nop 1
	v_add_f32_dpp v19, v18, v18 quad_perm:[1,0,3,2] row_mask:0xf bank_mask:0xf
	v_or_b32_e32 v18, s10, v30
	v_lshrrev_b32_e32 v25, 3, v18
	v_lshlrev_b32_e32 v30, 7, v30
	s_waitcnt lgkmcnt(0)
	s_nop 1
	v_add_f32_dpp v19, v19, v19 quad_perm:[2,3,0,1] row_mask:0xf bank_mask:0xf
	v_and_b32_e32 v24, 0x1ffffff0, v25
	v_add_u32_e32 v24, v24, v21
	v_ashrrev_i32_e32 v25, 31, v24
	v_lshlrev_b64 v[24:25], 14, v[24:25]
	s_waitcnt lgkmcnt(0)
	s_nop 1
	v_add_f32_dpp v19, v19, v19 row_half_mirror row_mask:0xf bank_mask:0xf
	v_lshl_add_u64 v[24:25], s[92:93], 0, v[24:25]
	v_mov_b32_e32 v31, v115
	v_lshl_add_u64 v[30:31], v[24:25], 0, v[30:31]
	v_lshl_add_u64 v[30:31], v[30:31], 0, v[114:115]
	s_waitcnt lgkmcnt(0)
	s_nop 1
	v_add_f32_dpp v19, v19, v19 row_mirror row_mask:0xf bank_mask:0xf
	ds_bpermute_b32 v24, v168, v19
	global_store_dwordx2 v[30:31], v[28:29], off
	s_and_saveexec_b64 s[16:17], s[4:5]
	s_cbranch_execz .LBB0_767
	s_waitcnt lgkmcnt(0)
	v_add_f32_e32 v24, v19, v24
	v_lshlrev_b32_e32 v18, 6, v18
	v_mov_b32_e32 v25, v115
	global_store_dwordx2 v18, v[24:25], s[6:7]
.LBB0_767:
	s_or_b64 exec, exec, s[16:17]
	s_waitcnt lgkmcnt(0)
	ds_read_b128 v[24:27], v23 offset:8448
	s_waitcnt vmcnt(7)
	v_and_b32_e32 v19, 0xffff0000, v16
	v_lshlrev_b32_e32 v18, 16, v16
	v_and_b32_e32 v29, 0xffff0000, v17
	v_lshlrev_b32_e32 v28, 16, v17
	s_waitcnt lgkmcnt(0)
	v_pk_add_f32 v[24:25], v[24:25], v[18:19]
	v_pk_add_f32 v[26:27], v[26:27], v[28:29]
	v_mul_f32_e32 v16, v25, v25
	v_fmac_f32_e32 v16, v24, v24
	v_fmac_f32_e32 v16, v26, v26
	v_fmac_f32_e32 v16, v27, v27
	v_add_u32_e32 v28, 16, v22
	v_cvt_pk_bf16_f32 v24, v24, v25
	v_cvt_pk_bf16_f32 v25, v26, v27
	s_waitcnt lgkmcnt(0)
	s_nop 1
	v_add_f32_dpp v17, v16, v16 quad_perm:[1,0,3,2] row_mask:0xf bank_mask:0xf
	v_or_b32_e32 v16, s10, v28
	v_lshrrev_b32_e32 v19, 3, v16
	v_lshlrev_b32_e32 v28, 7, v28
	s_waitcnt lgkmcnt(0)
	s_nop 1
	v_add_f32_dpp v17, v17, v17 quad_perm:[2,3,0,1] row_mask:0xf bank_mask:0xf
	v_and_b32_e32 v18, 0x1ffffff0, v19
	v_add_u32_e32 v18, v18, v21
	v_ashrrev_i32_e32 v19, 31, v18
	v_lshlrev_b64 v[18:19], 14, v[18:19]
	s_waitcnt lgkmcnt(0)
	s_nop 1
	v_add_f32_dpp v17, v17, v17 row_half_mirror row_mask:0xf bank_mask:0xf
	v_lshl_add_u64 v[18:19], s[92:93], 0, v[18:19]
	v_mov_b32_e32 v29, v115
	v_lshl_add_u64 v[28:29], v[18:19], 0, v[28:29]
	v_lshl_add_u64 v[28:29], v[28:29], 0, v[114:115]
	s_waitcnt lgkmcnt(0)
	s_nop 1
	v_add_f32_dpp v17, v17, v17 row_mirror row_mask:0xf bank_mask:0xf
	ds_bpermute_b32 v18, v168, v17
	global_store_dwordx2 v[28:29], v[24:25], off
	s_and_saveexec_b64 s[16:17], s[4:5]
	s_cbranch_execz .LBB0_769
	s_waitcnt lgkmcnt(0)
	v_add_f32_e32 v18, v17, v18
	v_lshlrev_b32_e32 v16, 6, v16
	v_mov_b32_e32 v19, v115
	global_store_dwordx2 v16, v[18:19], s[6:7]
.LBB0_769:
	s_or_b64 exec, exec, s[16:17]
	s_waitcnt lgkmcnt(0)
	ds_read_b128 v[16:19], v23 offset:12672
	s_waitcnt vmcnt(7)
	v_and_b32_e32 v25, 0xffff0000, v14
	v_lshlrev_b32_e32 v24, 16, v14
	v_and_b32_e32 v27, 0xffff0000, v15
	v_lshlrev_b32_e32 v26, 16, v15
	s_waitcnt lgkmcnt(0)
	v_pk_add_f32 v[24:25], v[16:17], v[24:25]
	v_pk_add_f32 v[18:19], v[18:19], v[26:27]
	v_mul_f32_e32 v14, v25, v25
	v_fmac_f32_e32 v14, v24, v24
	v_fmac_f32_e32 v14, v18, v18
	v_fmac_f32_e32 v14, v19, v19
	v_add_u32_e32 v26, 24, v22
	v_cvt_pk_bf16_f32 v24, v24, v25
	v_cvt_pk_bf16_f32 v25, v18, v19
	s_waitcnt lgkmcnt(0)
	s_nop 1
	v_add_f32_dpp v15, v14, v14 quad_perm:[1,0,3,2] row_mask:0xf bank_mask:0xf
	v_or_b32_e32 v14, s10, v26
	v_lshrrev_b32_e32 v17, 3, v14
	v_lshlrev_b32_e32 v26, 7, v26
	s_waitcnt lgkmcnt(0)
	s_nop 1
	v_add_f32_dpp v15, v15, v15 quad_perm:[2,3,0,1] row_mask:0xf bank_mask:0xf
	v_and_b32_e32 v16, 0x1ffffff0, v17
	v_add_u32_e32 v16, v16, v21
	v_ashrrev_i32_e32 v17, 31, v16
	v_lshlrev_b64 v[16:17], 14, v[16:17]
	s_waitcnt lgkmcnt(0)
	s_nop 1
	v_add_f32_dpp v15, v15, v15 row_half_mirror row_mask:0xf bank_mask:0xf
	v_lshl_add_u64 v[16:17], s[92:93], 0, v[16:17]
	v_mov_b32_e32 v27, v115
	v_lshl_add_u64 v[26:27], v[16:17], 0, v[26:27]
	v_lshl_add_u64 v[26:27], v[26:27], 0, v[114:115]
	s_waitcnt lgkmcnt(0)
	s_nop 1
	v_add_f32_dpp v15, v15, v15 row_mirror row_mask:0xf bank_mask:0xf
	ds_bpermute_b32 v16, v168, v15
	global_store_dwordx2 v[26:27], v[24:25], off
	s_and_saveexec_b64 s[16:17], s[4:5]
	s_cbranch_execz .LBB0_771
	s_waitcnt lgkmcnt(0)
	v_add_f32_e32 v16, v15, v16
	v_lshlrev_b32_e32 v14, 6, v14
	v_mov_b32_e32 v17, v115
	global_store_dwordx2 v14, v[16:17], s[6:7]
.LBB0_771:
	s_or_b64 exec, exec, s[16:17]
	s_waitcnt lgkmcnt(0)
	ds_read_b128 v[14:17], v23 offset:16896
	s_waitcnt vmcnt(7)
	v_and_b32_e32 v19, 0xffff0000, v12
	v_lshlrev_b32_e32 v18, 16, v12
	v_and_b32_e32 v25, 0xffff0000, v13
	v_lshlrev_b32_e32 v24, 16, v13
	s_waitcnt lgkmcnt(0)
	v_pk_add_f32 v[18:19], v[14:15], v[18:19]
	v_pk_add_f32 v[16:17], v[16:17], v[24:25]
	v_mul_f32_e32 v12, v19, v19
	v_fmac_f32_e32 v12, v18, v18
	v_fmac_f32_e32 v12, v16, v16
	v_fmac_f32_e32 v12, v17, v17
	v_or_b32_e32 v24, 32, v22
	v_cvt_pk_bf16_f32 v18, v18, v19
	v_cvt_pk_bf16_f32 v19, v16, v17
	s_waitcnt lgkmcnt(0)
	s_nop 1
	v_add_f32_dpp v13, v12, v12 quad_perm:[1,0,3,2] row_mask:0xf bank_mask:0xf
	v_or_b32_e32 v12, s10, v24
	v_lshrrev_b32_e32 v15, 3, v12
	v_lshlrev_b32_e32 v24, 7, v24
	s_waitcnt lgkmcnt(0)
	s_nop 1
	v_add_f32_dpp v13, v13, v13 quad_perm:[2,3,0,1] row_mask:0xf bank_mask:0xf
	v_and_b32_e32 v14, 0x1ffffff0, v15
	v_add_u32_e32 v14, v14, v21
	v_ashrrev_i32_e32 v15, 31, v14
	v_lshlrev_b64 v[14:15], 14, v[14:15]
	s_waitcnt lgkmcnt(0)
	s_nop 1
	v_add_f32_dpp v13, v13, v13 row_half_mirror row_mask:0xf bank_mask:0xf
	v_lshl_add_u64 v[14:15], s[92:93], 0, v[14:15]
	v_mov_b32_e32 v25, v115
	v_lshl_add_u64 v[24:25], v[14:15], 0, v[24:25]
	v_lshl_add_u64 v[24:25], v[24:25], 0, v[114:115]
	s_waitcnt lgkmcnt(0)
	s_nop 1
	v_add_f32_dpp v13, v13, v13 row_mirror row_mask:0xf bank_mask:0xf
	ds_bpermute_b32 v14, v168, v13
	global_store_dwordx2 v[24:25], v[18:19], off
	s_and_saveexec_b64 s[16:17], s[4:5]
	s_cbranch_execz .LBB0_773
	s_waitcnt lgkmcnt(0)
	v_add_f32_e32 v14, v13, v14
	v_lshlrev_b32_e32 v12, 6, v12
	v_mov_b32_e32 v15, v115
	global_store_dwordx2 v12, v[14:15], s[6:7]
.LBB0_773:
	s_or_b64 exec, exec, s[16:17]
	s_waitcnt lgkmcnt(0)
	ds_read_b128 v[12:15], v23 offset:21120
	s_waitcnt vmcnt(7)
	v_and_b32_e32 v17, 0xffff0000, v10
	v_lshlrev_b32_e32 v16, 16, v10
	v_and_b32_e32 v19, 0xffff0000, v11
	v_lshlrev_b32_e32 v18, 16, v11
	s_waitcnt lgkmcnt(0)
	v_pk_add_f32 v[16:17], v[12:13], v[16:17]
	v_pk_add_f32 v[14:15], v[14:15], v[18:19]
	v_mul_f32_e32 v10, v17, v17
	v_fmac_f32_e32 v10, v16, v16
	v_fmac_f32_e32 v10, v14, v14
	v_fmac_f32_e32 v10, v15, v15
	v_add_u32_e32 v18, 40, v22
	v_cvt_pk_bf16_f32 v16, v16, v17
	v_cvt_pk_bf16_f32 v17, v14, v15
	s_waitcnt lgkmcnt(0)
	s_nop 1
	v_add_f32_dpp v11, v10, v10 quad_perm:[1,0,3,2] row_mask:0xf bank_mask:0xf
	v_add_u32_e32 v10, s10, v18
	v_lshrrev_b32_e32 v13, 3, v10
	v_and_b32_e32 v13, 0x1ffffff0, v13
	v_lshlrev_b32_e32 v18, 7, v18
	s_waitcnt lgkmcnt(0)
	s_nop 1
	v_add_f32_dpp v11, v11, v11 quad_perm:[2,3,0,1] row_mask:0xf bank_mask:0xf
	v_add_u32_e32 v12, v13, v21
	v_ashrrev_i32_e32 v13, 31, v12
	v_lshlrev_b64 v[12:13], 14, v[12:13]
	v_lshl_add_u64 v[12:13], s[92:93], 0, v[12:13]
	s_waitcnt lgkmcnt(0)
	s_nop 1
	v_add_f32_dpp v11, v11, v11 row_half_mirror row_mask:0xf bank_mask:0xf
	v_and_b32_e32 v18, 0x3f80, v18
	v_mov_b32_e32 v19, v115
	v_lshl_add_u64 v[18:19], v[12:13], 0, v[18:19]
	v_lshl_add_u64 v[18:19], v[18:19], 0, v[114:115]
	s_waitcnt lgkmcnt(0)
	s_nop 1
	v_add_f32_dpp v11, v11, v11 row_mirror row_mask:0xf bank_mask:0xf
	ds_bpermute_b32 v12, v168, v11
	global_store_dwordx2 v[18:19], v[16:17], off
	s_and_saveexec_b64 s[16:17], s[4:5]
	s_cbranch_execz .LBB0_775
	s_waitcnt lgkmcnt(0)
	v_add_f32_e32 v12, v11, v12
	v_lshlrev_b32_e32 v10, 6, v10
	v_mov_b32_e32 v13, v115
	global_store_dwordx2 v10, v[12:13], s[6:7]
.LBB0_775:
	s_or_b64 exec, exec, s[16:17]
	s_waitcnt lgkmcnt(0)
	ds_read_b128 v[10:13], v23 offset:25344
	s_waitcnt vmcnt(7)
	v_and_b32_e32 v15, 0xffff0000, v8
	v_lshlrev_b32_e32 v14, 16, v8
	v_and_b32_e32 v17, 0xffff0000, v9
	v_lshlrev_b32_e32 v16, 16, v9
	s_waitcnt lgkmcnt(0)
	v_pk_add_f32 v[14:15], v[10:11], v[14:15]
	v_pk_add_f32 v[12:13], v[12:13], v[16:17]
	v_mul_f32_e32 v8, v15, v15
	v_fmac_f32_e32 v8, v14, v14
	v_fmac_f32_e32 v8, v12, v12
	v_fmac_f32_e32 v8, v13, v13
	v_add_u32_e32 v16, 48, v22
	v_cvt_pk_bf16_f32 v14, v14, v15
	v_cvt_pk_bf16_f32 v15, v12, v13
	s_waitcnt lgkmcnt(0)
	s_nop 1
	v_add_f32_dpp v9, v8, v8 quad_perm:[1,0,3,2] row_mask:0xf bank_mask:0xf
	v_add_u32_e32 v8, s10, v16
	v_lshrrev_b32_e32 v11, 3, v8
	v_and_b32_e32 v11, 0x1ffffff0, v11
	v_lshlrev_b32_e32 v16, 7, v16
	s_waitcnt lgkmcnt(0)
	s_nop 1
	v_add_f32_dpp v9, v9, v9 quad_perm:[2,3,0,1] row_mask:0xf bank_mask:0xf
	v_add_u32_e32 v10, v11, v21
	v_ashrrev_i32_e32 v11, 31, v10
	v_lshlrev_b64 v[10:11], 14, v[10:11]
	v_lshl_add_u64 v[10:11], s[92:93], 0, v[10:11]
	s_waitcnt lgkmcnt(0)
	s_nop 1
	v_add_f32_dpp v9, v9, v9 row_half_mirror row_mask:0xf bank_mask:0xf
	v_and_b32_e32 v16, 0x3f80, v16
	v_mov_b32_e32 v17, v115
	v_lshl_add_u64 v[16:17], v[10:11], 0, v[16:17]
	v_lshl_add_u64 v[16:17], v[16:17], 0, v[114:115]
	s_waitcnt lgkmcnt(0)
	s_nop 1
	v_add_f32_dpp v9, v9, v9 row_mirror row_mask:0xf bank_mask:0xf
	ds_bpermute_b32 v10, v168, v9
	global_store_dwordx2 v[16:17], v[14:15], off
	s_and_saveexec_b64 s[16:17], s[4:5]
	s_cbranch_execz .LBB0_777
	s_waitcnt lgkmcnt(0)
	v_add_f32_e32 v10, v9, v10
	v_lshlrev_b32_e32 v8, 6, v8
	v_mov_b32_e32 v11, v115
	global_store_dwordx2 v8, v[10:11], s[6:7]
.LBB0_777:
	s_or_b64 exec, exec, s[16:17]
	s_waitcnt lgkmcnt(0)
	ds_read_b128 v[8:11], v23 offset:29568
	s_waitcnt vmcnt(7)
	v_and_b32_e32 v13, 0xffff0000, v6
	v_lshlrev_b32_e32 v12, 16, v6
	v_and_b32_e32 v15, 0xffff0000, v7
	v_lshlrev_b32_e32 v14, 16, v7
	s_waitcnt lgkmcnt(0)
	v_pk_add_f32 v[12:13], v[8:9], v[12:13]
	v_pk_add_f32 v[10:11], v[10:11], v[14:15]
	v_mul_f32_e32 v6, v13, v13
	v_fmac_f32_e32 v6, v12, v12
	v_fmac_f32_e32 v6, v10, v10
	v_fmac_f32_e32 v6, v11, v11
	v_add_u32_e32 v14, 56, v22
	v_cvt_pk_bf16_f32 v12, v12, v13
	v_cvt_pk_bf16_f32 v13, v10, v11
	s_waitcnt lgkmcnt(0)
	s_nop 1
	v_add_f32_dpp v7, v6, v6 quad_perm:[1,0,3,2] row_mask:0xf bank_mask:0xf
	v_add_u32_e32 v6, s10, v14
	v_lshrrev_b32_e32 v9, 3, v6
	v_and_b32_e32 v9, 0x1ffffff0, v9
	v_lshlrev_b32_e32 v14, 7, v14
	s_waitcnt lgkmcnt(0)
	s_nop 1
	v_add_f32_dpp v7, v7, v7 quad_perm:[2,3,0,1] row_mask:0xf bank_mask:0xf
	v_add_u32_e32 v8, v9, v21
	v_ashrrev_i32_e32 v9, 31, v8
	v_lshlrev_b64 v[8:9], 14, v[8:9]
	v_lshl_add_u64 v[8:9], s[92:93], 0, v[8:9]
	s_waitcnt lgkmcnt(0)
	s_nop 1
	v_add_f32_dpp v7, v7, v7 row_half_mirror row_mask:0xf bank_mask:0xf
	v_and_b32_e32 v14, 0x3f80, v14
	v_mov_b32_e32 v15, v115
	v_lshl_add_u64 v[14:15], v[8:9], 0, v[14:15]
	v_lshl_add_u64 v[14:15], v[14:15], 0, v[114:115]
	s_waitcnt lgkmcnt(0)
	s_nop 1
	v_add_f32_dpp v7, v7, v7 row_mirror row_mask:0xf bank_mask:0xf
	ds_bpermute_b32 v8, v168, v7
	global_store_dwordx2 v[14:15], v[12:13], off
	s_and_saveexec_b64 s[16:17], s[4:5]
	s_cbranch_execz .LBB0_762
	s_waitcnt lgkmcnt(0)
	v_add_f32_e32 v8, v7, v8
	v_lshlrev_b32_e32 v6, 6, v6
	v_mov_b32_e32 v9, v115
	global_store_dwordx2 v6, v[8:9], s[6:7]
	s_branch .LBB0_762
